# fixup-tile-1-batched-loads
# baseline (speedup 1.0000x reference)
; template <int MODE>
; __device__ void fixup_mine(const pg8::StaticOrder& S, const float* cw, int C, int voff, int nch, const float* PART, const float* TAIL, bf16_t* O, int ldo, const bf16_t* BG) {
;     pg8::Unit u; int last_pm = -1;
;     for (int i = 0; S.next(i, u); ++i) { if (u.pm != last_pm) fixup_tile<MODE>(u.pm, cw, C, voff, nch, PART, TAIL, O, ldo, BG); last_pm = u.pm; }
; __global__ void __launch_bounds__(512, 2) fwd_megakernel(Params p_unused) {
;     ...
;                 const Params* q = kparams();
;                 pg8::Gemm g{WSP(bf16_t, WS_ACT) + (size_t)M * D, WSP(bf16_t, WS_WSOUT), M, D, D, D, NOGRP, 0}; pg8::StaticOrder S; S.init(M, D, G, bid);
;                 fixup_mine<1>(S, q->sconv_w, D, 0, D, WSP(float, WS_PART), WSP(float, WS_TAIL), WSP(bf16_t, WS_ACT) + (size_t)M * D, D, WSP(bf16_t, WS_ACT));
.LBB0_580:
	s_mov_b32 s0, 0
	s_ashr_i32 s1, s0, 31
	s_add_u32 s0, s96, s0
	s_addc_u32 s1, s97, s1
	s_load_dwordx2 s[4:5], s[0:1], 0x90
	s_load_dwordx2 s[8:9], s[0:1], 0x48
	s_mov_b32 s17, -1
	s_mov_b32 s16, 0
	s_waitcnt lgkmcnt(0)
	s_add_u32 s6, s4, 0x1a630000
	s_addc_u32 s7, s5, 0
	s_add_u32 s10, s4, 0x28630000
	s_addc_u32 s11, s5, 0
	s_add_u32 s0, s4, 0x29130000
	s_addc_u32 s1, s5, 0
	s_add_u32 s52, s4, 0x12630000
	s_addc_u32 s53, s5, 0
	s_add_u32 s54, s8, 0x2000
	s_addc_u32 s55, s9, 0
	s_branch .LBB0_584
.LBB0_582:
	s_add_i32 s16, s16, 1
	s_mov_b64 s[60:61], 0

; __device__ __forceinline__ float silu_f(float g) { return g * __builtin_amdgcn_rcpf(1.0f + __builtin_amdgcn_exp2f(-1.44269504089f * g)); }
;     __device__ bool next(int i, Unit& u) const {
;         const long L = (long)i * G + c; if (L >= nwg) return false;
;         int wgid = (int)L; { const int q = nwg / NXCD, r = nwg % NXCD, xcd = wgid % NXCD, off = wgid / NXCD; wgid = (xcd < r ? xcd * (q + 1) : r * (q + 1) + (xcd - r) * q) + off; }
;         const int nig = WGM * nN, gid = wgid / nig, fm = gid * WGM, gsz = (nM - fm) < WGM ? (nM - fm) : WGM;
;         u.pm = fm + ((wgid % nig) % gsz); u.pn = (wgid % nig) / gsz; return true;
; template <int MODE>
; __device__ void fixup_tile(int pm, const float* cw, int C, int voff, int nch, const float* PART, const float* TAIL, bf16_t* O, int ldo, const bf16_t* BG) {
;     const int nq = nch / 4;
;     int tid = threadIdx.x; asm volatile("" : "+v"(tid));
;     for (int i = tid; i < 2 * nq; i += 512) {
;         const int r = i / nq, ch = (i - r * nq) * 4;
;         const size_t row = (size_t)pm * 256 + r;
;         f32x4 val[2];
; #pragma unroll
;         for (int s = 0; s < (MODE == 0 ? 2 : 1); ++s) {
;             const int co = (s ? voff : 0) + ch;
;             f32x4 a = *(const f32x4*)(PART + (size_t)(pm * 2 + r) * C + co);
;             if ((pm & 63) != 0) {
;                 const f32x4 t1 = *(const f32x4*)(TAIL + (size_t)((pm - 1) * 2 + 1) * C + co);
;                 const f32x4 w0 = *(const f32x4*)(cw + co);
;                 if (r == 0) { const f32x4 t2 = *(const f32x4*)(TAIL + (size_t)((pm - 1) * 2 + 0) * C + co); const f32x4 w1 = *(const f32x4*)(cw + C + co); a += w1 * t1 + w0 * t2; }
;                 else a += w0 * t1;
;             }
;             val[s] = a;
;         }
;         f32x4 o;
;         if (MODE == 0) {
; #pragma unroll
;             for (int j = 0; j < 4; ++j) o[j] = pg8::silu_f(val[0][j]) * val[1][j];
;         } else {
;             const u32x2 bg = *(const u32x2*)(BG + row * D + ch);
;             o[0] = __uint_as_float(bg.x << 16) * val[0][0]; o[1] = __uint_as_float(bg.x & 0xffff0000u) * val[0][1];
;             o[2] = __uint_as_float(bg.y << 16) * val[0][2]; o[3] = __uint_as_float(bg.y & 0xffff0000u) * val[0][3];
;         }
;         u32x2 w; w.x = cvt_pk_bf16(o[0], o[1]); w.y = cvt_pk_bf16(o[2], o[3]);
;         *(u32x2*)(O + img_off((int)row, ch, ldo)) = w;
;     }
.LBB0_589:
	s_ashr_i32 s21, s21, 3
	s_add_i32 s21, s24, s21
	s_ashr_i32 s22, s21, 31
	s_lshr_b32 s22, s22, 26
	s_add_i32 s22, s21, s22
	s_ashr_i32 s24, s22, 6
	s_lshl_b32 s24, s24, 3
	s_sub_i32 s25, 0x80, s24
	s_min_i32 s25, s25, 8
	s_abs_i32 s25, s25
	v_cvt_f32_u32_e32 v0, s25
	s_sub_i32 s26, 0, s25
	s_andn2_b32 s22, s22, 63
	s_sub_i32 s21, s21, s22
	v_rcp_iflag_f32_e32 v0, v0
	s_ashr_i32 s22, s21, 31
	s_abs_i32 s21, s21
	v_mul_f32_e32 v0, 0x4f7ffffe, v0
	v_cvt_u32_f32_e32 v0, v0
	s_nop 0
	v_readfirstlane_b32 s27, v0
	s_mul_i32 s26, s26, s27
	s_mul_hi_u32 s26, s27, s26
	s_add_i32 s27, s27, s26
	s_mul_hi_u32 s26, s21, s27
	s_mul_i32 s26, s26, s25
	s_sub_i32 s21, s21, s26
	s_sub_i32 s26, s21, s25
	s_cmp_ge_u32 s21, s25
	s_cselect_b32 s21, s26, s21
	s_sub_i32 s26, s21, s25
	s_cmp_ge_u32 s21, s25
	s_cselect_b32 s21, s26, s21
	s_xor_b32 s21, s21, s22
	s_sub_i32 s21, s21, s22
	s_add_i32 s56, s24, s21
	s_cmp_eq_u32 s56, s17
	s_cbranch_scc1 .LBB0_582
	s_and_b32 s60, s56, 63
	s_cmp_lg_u32 s60, 0
	s_cselect_b64 s[64:65], -1, 0
	v_lshlrev_b32_e32 v12, 4, v235
	v_lshlrev_b32_e32 v14, 3, v235
	s_lshl_b32 s60, s56, 14
	s_add_u32 s62, s10, s60
	s_addc_u32 s63, s11, 0
	s_add_i32 s61, s60, 0xffffe000
	s_add_u32 s66, s0, s61
	s_addc_u32 s67, s1, 0
	s_add_i32 s61, s60, 0xffffc000
	s_add_u32 s68, s0, s61
	s_addc_u32 s69, s1, 0
	s_lshl_b32 s60, s56, 20
	s_add_u32 s70, s52, s60
	s_addc_u32 s71, s53, 0
	s_add_u32 s72, s6, s60
	s_addc_u32 s73, s7, 0
	v_add_u32_e32 v13, 0x2000, v12
	v_add_u32_e32 v15, 0x1000, v14
	global_load_dwordx4 v[20:23], v12, s[62:63]
	global_load_dwordx4 v[24:27], v13, s[62:63]
	global_load_dwordx2 v[44:45], v14, s[70:71]
	global_load_dwordx2 v[46:47], v15, s[70:71]
	s_andn2_b64 vcc, exec, s[64:65]
	s_cbranch_vccnz .Lfx1_ld
	global_load_dwordx4 v[28:31], v12, s[66:67]
	global_load_dwordx4 v[32:35], v12, s[68:69]
	global_load_dwordx4 v[36:39], v12, s[8:9]
	global_load_dwordx4 v[40:43], v12, s[54:55]
.Lfx1_ld:
	v_and_b32_e32 v48, -16, v235
	v_and_b32_e32 v49, 8, v235
	v_and_b32_e32 v50, 7, v235
	v_lshlrev_b32_e32 v48, 10, v48
	v_lshlrev_b32_e32 v49, 7, v49
	v_lshlrev_b32_e32 v50, 3, v50
	v_or3_b32 v16, v48, v49, v50
	s_waitcnt vmcnt(0)
	s_andn2_b64 vcc, exec, s[64:65]
	s_cbranch_vccnz .Lfx1_nohalo
	v_pk_mul_f32 v[40:41], v[28:29], v[40:41]
	v_pk_mul_f32 v[42:43], v[30:31], v[42:43]
	v_pk_fma_f32 v[40:41], v[36:37], v[32:33], v[40:41]
	v_pk_fma_f32 v[42:43], v[38:39], v[34:35], v[42:43]
	v_pk_mul_f32 v[28:29], v[28:29], v[36:37]
	v_pk_mul_f32 v[30:31], v[30:31], v[38:39]
	v_pk_add_f32 v[20:21], v[20:21], v[40:41]
	v_pk_add_f32 v[22:23], v[22:23], v[42:43]
	v_pk_add_f32 v[24:25], v[24:25], v[28:29]
	v_pk_add_f32 v[26:27], v[26:27], v[30:31]
.Lfx1_nohalo:
	v_lshlrev_b32_e32 v48, 16, v44
	v_and_b32_e32 v49, 0xffff0000, v44
	v_lshlrev_b32_e32 v50, 16, v45
	v_and_b32_e32 v51, 0xffff0000, v45
	v_mul_f32_e32 v20, v20, v48
	v_mul_f32_e32 v21, v21, v49
	v_mul_f32_e32 v22, v22, v50
	v_mul_f32_e32 v23, v23, v51
	v_cvt_pk_bf16_f32 v52, v20, v21
	v_cvt_pk_bf16_f32 v53, v22, v23
	global_store_dwordx2 v16, v[52:53], s[72:73]
	v_lshlrev_b32_e32 v48, 16, v46
	v_and_b32_e32 v49, 0xffff0000, v46
	v_lshlrev_b32_e32 v50, 16, v47
	v_and_b32_e32 v51, 0xffff0000, v47
	v_mul_f32_e32 v24, v24, v48
	v_mul_f32_e32 v25, v25, v49
	v_mul_f32_e32 v26, v26, v50
	v_mul_f32_e32 v27, v27, v51
	v_cvt_pk_bf16_f32 v54, v24, v25
	v_cvt_pk_bf16_f32 v55, v26, v27
	global_store_dwordx2 v16, v[54:55], s[72:73] offset:64
	s_branch .LBB0_582
